# half units: the never-read A rows 128..255 stage buffers get one-dword DMAs of one hot line instead of full 16-byte-per-lane DMAs (same DMA count, same vmcnt waits)
# baseline (speedup 1.0000x reference)
.Lht_a0:
	global_load_lds_dword v135, s[38:39]
	s_add_i32 m0, s29, 0xe000
	s_nop 0
	global_load_lds_dword v135, s[38:39]
	s_branch .Lht_b0

.Lht_a2:
	global_load_lds_dword v135, s[42:43]
	s_mov_b32 m0, s46
	s_nop 0
	global_load_lds_dword v135, s[42:43]
	s_branch .Lht_b2

.LBB0_767:
	s_ashr_i32 s19, s18, 31
	s_lshl_b64 s[20:21], s[18:19], 19
	s_add_u32 s20, s24, s20
	s_addc_u32 s21, s25, s21
	s_cmp_eq_u32 s91, 2
	s_cselect_b32 s26, 0x40000, 0
	s_add_u32 s20, s20, s26
	s_addc_u32 s21, s21, 0
	s_and_b64 s[26:27], s[6:7], exec
	s_cselect_b32 s0, s21, s39
	s_cselect_b32 s19, s20, s38
	s_ashr_i32 s17, s16, 31
	s_lshl_b64 s[26:27], s[16:17], 19
	s_add_u32 s26, s64, s26
	s_addc_u32 s27, s65, s27
	s_and_b64 s[42:43], s[6:7], exec
	s_cselect_b32 s17, s27, s41
	s_cselect_b32 s66, s26, s40
	s_add_u32 s38, s38, 0x40080
	s_addc_u32 s39, s39, 0
	s_add_u32 s67, s40, 0x100
	s_addc_u32 s68, s41, 0
	s_mov_b32 s69, -2
	ds_read_b128 v[146:149], v153
	ds_read_b128 v[156:159], v153 offset:1024
	ds_read_b128 v[160:163], v153 offset:2048
	ds_read_b128 v[164:167], v153 offset:3072
	ds_read_b128 v[168:171], v154
	ds_read_b128 v[172:175], v154 offset:1024
	ds_read_b128 v[176:179], v154 offset:2048
	ds_read_b128 v[180:183], v154 offset:3072
	s_add_u32 s40, s38, 0xfffc0080
	s_addc_u32 s41, s39, -1
	s_cmp_eq_u32 s69, 12
	s_cselect_b32 s43, s0, s41
	s_cselect_b32 s42, s19, s40
	s_cselect_b32 s41, s17, s68
	s_cselect_b32 s40, s66, s67
	v_lshl_add_u64 v[216:217], s[38:39], 0, v[138:139]
	s_add_i32 m0, s29, 0xc000
	ds_read_b128 v[184:187], v155
	ds_read_b128 v[188:191], v155 offset:1024
	ds_read_b128 v[192:195], v155 offset:2048
	ds_read_b128 v[196:199], v155 offset:3072
	ds_read_b128 v[200:203], v155 offset:4096
	ds_read_b128 v[204:207], v155 offset:5120
	ds_read_b128 v[208:211], v155 offset:6144
	ds_read_b128 v[212:215], v155 offset:7168
	s_cmp_lg_u32 s90, 0
	s_cbranch_scc1 .Lht_a0
	global_load_lds_dwordx4 v[216:217], off
	v_lshl_add_u64 v[216:217], s[38:39], 0, v[140:141]
	s_add_i32 m0, s29, 0xe000
	s_nop 0
	global_load_lds_dwordx4 v[216:217], off
.Lht_b0:
	s_waitcnt vmcnt(8)
	s_waitcnt lgkmcnt(0)
	s_setprio 1
	s_waitcnt lgkmcnt(0)
	s_barrier
	v_mfma_f32_16x16x32_bf16 v[126:129], v[146:149], v[184:187], 0
	v_mfma_f32_16x16x32_bf16 v[122:125], v[160:163], v[184:187], 0
	v_mfma_f32_16x16x32_bf16 v[110:113], v[146:149], v[192:195], 0
	v_mfma_f32_16x16x32_bf16 v[106:109], v[160:163], v[192:195], 0
	v_mfma_f32_16x16x32_bf16 v[94:97], v[146:149], v[200:203], 0
	v_mfma_f32_16x16x32_bf16 v[90:93], v[160:163], v[200:203], 0
	v_mfma_f32_16x16x32_bf16 v[78:81], v[146:149], v[208:211], 0
	v_mfma_f32_16x16x32_bf16 v[74:77], v[160:163], v[208:211], 0
	v_mfma_f32_16x16x32_bf16 v[118:121], v[168:171], v[184:187], 0
	v_mfma_f32_16x16x32_bf16 v[114:117], v[176:179], v[184:187], 0
	v_mfma_f32_16x16x32_bf16 v[102:105], v[168:171], v[192:195], 0
	v_mfma_f32_16x16x32_bf16 v[98:101], v[176:179], v[192:195], 0
	v_mfma_f32_16x16x32_bf16 v[86:89], v[168:171], v[200:203], 0
	v_mfma_f32_16x16x32_bf16 v[82:85], v[176:179], v[200:203], 0
	v_mfma_f32_16x16x32_bf16 v[70:73], v[168:171], v[208:211], 0
	v_mfma_f32_16x16x32_bf16 v[66:69], v[176:179], v[208:211], 0
	v_mfma_f32_16x16x32_bf16 v[126:129], v[156:159], v[188:191], v[126:129]
	v_mfma_f32_16x16x32_bf16 v[122:125], v[164:167], v[188:191], v[122:125]
	v_mfma_f32_16x16x32_bf16 v[110:113], v[156:159], v[196:199], v[110:113]
	v_mfma_f32_16x16x32_bf16 v[106:109], v[164:167], v[196:199], v[106:109]
	v_mfma_f32_16x16x32_bf16 v[94:97], v[156:159], v[204:207], v[94:97]
	v_mfma_f32_16x16x32_bf16 v[90:93], v[164:167], v[204:207], v[90:93]
	v_mfma_f32_16x16x32_bf16 v[78:81], v[156:159], v[212:215], v[78:81]
	v_mfma_f32_16x16x32_bf16 v[74:77], v[164:167], v[212:215], v[74:77]
	v_mfma_f32_16x16x32_bf16 v[118:121], v[172:175], v[188:191], v[118:121]
	v_mfma_f32_16x16x32_bf16 v[114:117], v[180:183], v[188:191], v[114:117]
	v_mfma_f32_16x16x32_bf16 v[102:105], v[172:175], v[196:199], v[102:105]
	v_mfma_f32_16x16x32_bf16 v[98:101], v[180:183], v[196:199], v[98:101]
	v_mfma_f32_16x16x32_bf16 v[86:89], v[172:175], v[204:207], v[86:89]
	v_mfma_f32_16x16x32_bf16 v[82:85], v[180:183], v[204:207], v[82:85]
	v_mfma_f32_16x16x32_bf16 v[70:73], v[172:175], v[212:215], v[70:73]
	v_mfma_f32_16x16x32_bf16 v[66:69], v[180:183], v[212:215], v[66:69]
	s_setprio 0
	s_barrier
	s_add_i32 s70, s51, s1
	v_lshl_add_u64 v[216:217], s[40:41], 0, v[134:135]
	s_mov_b32 m0, s70
	s_cmp_lg_u32 s90, 0
	s_cbranch_scc1 .Lht_rd0
	ds_read_b128 v[184:187], v155 offset:16384
	ds_read_b128 v[188:191], v155 offset:17408
	ds_read_b128 v[192:195], v155 offset:18432
	ds_read_b128 v[196:199], v155 offset:19456
	ds_read_b128 v[200:203], v155 offset:20480
	ds_read_b128 v[204:207], v155 offset:21504
	ds_read_b128 v[208:211], v155 offset:22528
	ds_read_b128 v[212:215], v155 offset:23552

.Lht_mm0:
	s_setprio 0
	s_barrier
	s_add_i32 s70, 0, 0x18000
	s_add_i32 s71, 0, 0x1c000
	v_add_u32_e32 v164, s70, v151
	v_add_u32_e32 v180, s71, v151
	ds_read_b128 v[146:149], v164
	ds_read_b128 v[156:159], v164 offset:1024
	ds_read_b128 v[160:163], v164 offset:2048
	ds_read_b128 v[164:167], v164 offset:3072
	ds_read_b128 v[168:171], v180
	ds_read_b128 v[172:175], v180 offset:1024
	ds_read_b128 v[176:179], v180 offset:2048
	ds_read_b128 v[180:183], v180 offset:3072
	s_add_u32 s42, s42, 0x40000
	s_addc_u32 s43, s43, 0
	s_mov_b32 m0, s45
	v_lshl_add_u64 v[224:225], s[42:43], 0, v[136:137]
	ds_read_b128 v[184:187], v155 offset:32768
	ds_read_b128 v[188:191], v155 offset:33792
	ds_read_b128 v[192:195], v155 offset:34816
	ds_read_b128 v[196:199], v155 offset:35840
	ds_read_b128 v[200:203], v155 offset:36864
	ds_read_b128 v[204:207], v155 offset:37888
	ds_read_b128 v[208:211], v155 offset:38912
	ds_read_b128 v[212:215], v155 offset:39936
	s_cmp_lg_u32 s90, 0
	s_cbranch_scc1 .Lht_a2
	global_load_lds_dwordx4 v[224:225], off
	v_lshl_add_u64 v[224:225], s[42:43], 0, v[132:133]
	s_mov_b32 m0, s46
	s_nop 0
	global_load_lds_dwordx4 v[224:225], off
.Lht_b2:
	s_waitcnt vmcnt(8)
	s_waitcnt lgkmcnt(0)
	s_setprio 1
	s_waitcnt lgkmcnt(0)
	s_barrier
	v_mfma_f32_16x16x32_bf16 v[126:129], v[146:149], v[184:187], v[126:129]
	v_mfma_f32_16x16x32_bf16 v[122:125], v[160:163], v[184:187], v[122:125]
	v_mfma_f32_16x16x32_bf16 v[110:113], v[146:149], v[192:195], v[110:113]
	v_mfma_f32_16x16x32_bf16 v[106:109], v[160:163], v[192:195], v[106:109]
	v_mfma_f32_16x16x32_bf16 v[94:97], v[146:149], v[200:203], v[94:97]
	v_mfma_f32_16x16x32_bf16 v[90:93], v[160:163], v[200:203], v[90:93]
	v_mfma_f32_16x16x32_bf16 v[78:81], v[146:149], v[208:211], v[78:81]
	v_mfma_f32_16x16x32_bf16 v[74:77], v[160:163], v[208:211], v[74:77]
	v_mfma_f32_16x16x32_bf16 v[118:121], v[168:171], v[184:187], v[118:121]
	v_mfma_f32_16x16x32_bf16 v[114:117], v[176:179], v[184:187], v[114:117]
	v_mfma_f32_16x16x32_bf16 v[102:105], v[168:171], v[192:195], v[102:105]
	v_mfma_f32_16x16x32_bf16 v[98:101], v[176:179], v[192:195], v[98:101]
	v_mfma_f32_16x16x32_bf16 v[86:89], v[168:171], v[200:203], v[86:89]
	v_mfma_f32_16x16x32_bf16 v[82:85], v[176:179], v[200:203], v[82:85]
	v_mfma_f32_16x16x32_bf16 v[70:73], v[168:171], v[208:211], v[70:73]
	v_mfma_f32_16x16x32_bf16 v[66:69], v[176:179], v[208:211], v[66:69]
	v_mfma_f32_16x16x32_bf16 v[126:129], v[156:159], v[188:191], v[126:129]
	v_mfma_f32_16x16x32_bf16 v[122:125], v[164:167], v[188:191], v[122:125]
	v_mfma_f32_16x16x32_bf16 v[110:113], v[156:159], v[196:199], v[110:113]
	v_mfma_f32_16x16x32_bf16 v[106:109], v[164:167], v[196:199], v[106:109]
	v_mfma_f32_16x16x32_bf16 v[94:97], v[156:159], v[204:207], v[94:97]
	v_mfma_f32_16x16x32_bf16 v[90:93], v[164:167], v[204:207], v[90:93]
	v_mfma_f32_16x16x32_bf16 v[78:81], v[156:159], v[212:215], v[78:81]
	v_mfma_f32_16x16x32_bf16 v[74:77], v[164:167], v[212:215], v[74:77]
	v_mfma_f32_16x16x32_bf16 v[118:121], v[172:175], v[188:191], v[118:121]
	v_mfma_f32_16x16x32_bf16 v[114:117], v[180:183], v[188:191], v[114:117]
	v_mfma_f32_16x16x32_bf16 v[102:105], v[172:175], v[196:199], v[102:105]
	v_mfma_f32_16x16x32_bf16 v[98:101], v[180:183], v[196:199], v[98:101]
	v_mfma_f32_16x16x32_bf16 v[86:89], v[172:175], v[204:207], v[86:89]
	v_mfma_f32_16x16x32_bf16 v[82:85], v[180:183], v[204:207], v[82:85]
	v_mfma_f32_16x16x32_bf16 v[70:73], v[172:175], v[212:215], v[70:73]
	v_mfma_f32_16x16x32_bf16 v[66:69], v[180:183], v[212:215], v[66:69]
	s_setprio 0
	s_barrier
	s_add_i32 s42, s70, s1
	v_lshl_add_u64 v[216:217], v[216:217], 0, s[12:13]
	s_mov_b32 m0, s42
	s_cmp_lg_u32 s90, 0
	s_cbranch_scc1 .Lht_rd2
	ds_read_b128 v[184:187], v155 offset:49152
	ds_read_b128 v[188:191], v155 offset:50176
	ds_read_b128 v[192:195], v155 offset:51200
	ds_read_b128 v[196:199], v155 offset:52224
	ds_read_b128 v[200:203], v155 offset:53248
	ds_read_b128 v[204:207], v155 offset:54272
	ds_read_b128 v[208:211], v155 offset:55296
	ds_read_b128 v[212:215], v155 offset:56320

.LBB0_768:
	ds_read_b128 v[146:149], v153
	ds_read_b128 v[156:159], v153 offset:1024
	ds_read_b128 v[160:163], v153 offset:2048
	ds_read_b128 v[164:167], v153 offset:3072
	ds_read_b128 v[168:171], v154
	ds_read_b128 v[172:175], v154 offset:1024
	ds_read_b128 v[176:179], v154 offset:2048
	ds_read_b128 v[180:183], v154 offset:3072
	s_add_u32 s40, s38, 0xfffc0080
	s_addc_u32 s41, s39, -1
	s_cmp_eq_u32 s69, 12
	s_cselect_b32 s43, s0, s41
	s_cselect_b32 s42, s19, s40
	s_cselect_b32 s41, s17, s68
	s_cselect_b32 s40, s66, s67
	v_lshl_add_u64 v[216:217], s[38:39], 0, v[138:139]
	s_add_i32 m0, s29, 0xc000
	ds_read_b128 v[184:187], v155
	ds_read_b128 v[188:191], v155 offset:1024
	ds_read_b128 v[192:195], v155 offset:2048
	ds_read_b128 v[196:199], v155 offset:3072
	ds_read_b128 v[200:203], v155 offset:4096
	ds_read_b128 v[204:207], v155 offset:5120
	ds_read_b128 v[208:211], v155 offset:6144
	ds_read_b128 v[212:215], v155 offset:7168
	s_cmp_lg_u32 s90, 0
	s_cbranch_scc1 .Lht_a1
	global_load_lds_dwordx4 v[216:217], off
	v_lshl_add_u64 v[216:217], s[38:39], 0, v[140:141]
	s_add_i32 m0, s29, 0xe000
	s_nop 0
	global_load_lds_dwordx4 v[216:217], off
.Lht_b1:
	s_waitcnt vmcnt(8)
	s_waitcnt lgkmcnt(0)
	s_setprio 1
	s_waitcnt lgkmcnt(0)
	s_barrier
	v_mfma_f32_16x16x32_bf16 v[126:129], v[146:149], v[184:187], v[126:129]
	v_mfma_f32_16x16x32_bf16 v[122:125], v[160:163], v[184:187], v[122:125]
	v_mfma_f32_16x16x32_bf16 v[110:113], v[146:149], v[192:195], v[110:113]
	v_mfma_f32_16x16x32_bf16 v[106:109], v[160:163], v[192:195], v[106:109]
	v_mfma_f32_16x16x32_bf16 v[94:97], v[146:149], v[200:203], v[94:97]
	v_mfma_f32_16x16x32_bf16 v[90:93], v[160:163], v[200:203], v[90:93]
	v_mfma_f32_16x16x32_bf16 v[78:81], v[146:149], v[208:211], v[78:81]
	v_mfma_f32_16x16x32_bf16 v[74:77], v[160:163], v[208:211], v[74:77]
	v_mfma_f32_16x16x32_bf16 v[118:121], v[168:171], v[184:187], v[118:121]
	v_mfma_f32_16x16x32_bf16 v[114:117], v[176:179], v[184:187], v[114:117]
	v_mfma_f32_16x16x32_bf16 v[102:105], v[168:171], v[192:195], v[102:105]
	v_mfma_f32_16x16x32_bf16 v[98:101], v[176:179], v[192:195], v[98:101]
	v_mfma_f32_16x16x32_bf16 v[86:89], v[168:171], v[200:203], v[86:89]
	v_mfma_f32_16x16x32_bf16 v[82:85], v[176:179], v[200:203], v[82:85]
	v_mfma_f32_16x16x32_bf16 v[70:73], v[168:171], v[208:211], v[70:73]
	v_mfma_f32_16x16x32_bf16 v[66:69], v[176:179], v[208:211], v[66:69]
	v_mfma_f32_16x16x32_bf16 v[126:129], v[156:159], v[188:191], v[126:129]
	v_mfma_f32_16x16x32_bf16 v[122:125], v[164:167], v[188:191], v[122:125]
	v_mfma_f32_16x16x32_bf16 v[110:113], v[156:159], v[196:199], v[110:113]
	v_mfma_f32_16x16x32_bf16 v[106:109], v[164:167], v[196:199], v[106:109]
	v_mfma_f32_16x16x32_bf16 v[94:97], v[156:159], v[204:207], v[94:97]
	v_mfma_f32_16x16x32_bf16 v[90:93], v[164:167], v[204:207], v[90:93]
	v_mfma_f32_16x16x32_bf16 v[78:81], v[156:159], v[212:215], v[78:81]
	v_mfma_f32_16x16x32_bf16 v[74:77], v[164:167], v[212:215], v[74:77]
	v_mfma_f32_16x16x32_bf16 v[118:121], v[172:175], v[188:191], v[118:121]
	v_mfma_f32_16x16x32_bf16 v[114:117], v[180:183], v[188:191], v[114:117]
	v_mfma_f32_16x16x32_bf16 v[102:105], v[172:175], v[196:199], v[102:105]
	v_mfma_f32_16x16x32_bf16 v[98:101], v[180:183], v[196:199], v[98:101]
	v_mfma_f32_16x16x32_bf16 v[86:89], v[172:175], v[204:207], v[86:89]
	v_mfma_f32_16x16x32_bf16 v[82:85], v[180:183], v[204:207], v[82:85]
	v_mfma_f32_16x16x32_bf16 v[70:73], v[172:175], v[212:215], v[70:73]
	v_mfma_f32_16x16x32_bf16 v[66:69], v[180:183], v[212:215], v[66:69]
	s_setprio 0
	s_barrier
	s_add_i32 s70, s51, s1
	v_lshl_add_u64 v[216:217], s[40:41], 0, v[134:135]
	s_mov_b32 m0, s70
	s_cmp_lg_u32 s90, 0
	s_cbranch_scc1 .Lht_rd1
	ds_read_b128 v[184:187], v155 offset:16384
	ds_read_b128 v[188:191], v155 offset:17408
	ds_read_b128 v[192:195], v155 offset:18432
	ds_read_b128 v[196:199], v155 offset:19456
	ds_read_b128 v[200:203], v155 offset:20480
	ds_read_b128 v[204:207], v155 offset:21504
	ds_read_b128 v[208:211], v155 offset:22528
	ds_read_b128 v[212:215], v155 offset:23552
